# v08: + near-diagonal softmax bias lookups 12 deep instead of 16 masked single lookups; compression MLP 2nd layer: one batched load round trip, double-buffered W2 fragments, K-norm gains prefetched
# speedup vs baseline: 1.0220x; 1.0031x over previous
.LBB0_1073:
	s_or_b64 exec, exec, s[0:1]
	v_readfirstlane_b32 s24, v6
	s_cmp_eq_u32 s24, 0
	v_mov_b32_e32 v73, v65
	v_readlane_b32 s64, v239, 35
	s_cselect_b64 s[4:5], -1, 0
	s_cmp_lg_u32 s24, 0
	v_lshl_add_u64 v[90:91], v[0:1], 0, v[72:73]
	v_lshl_add_u64 v[86:87], v[8:9], 0, v[72:73]
	v_readlane_b32 s48, v239, 19
	v_readlane_b32 s66, v239, 37
	v_readlane_b32 s67, v239, 38
	s_cselect_b64 s[26:27], -1, 0
	global_load_dwordx4 v[116:119], v[90:91], off
	global_load_dwordx4 v[120:123], v[90:91], off offset:16
	global_load_dwordx4 v[180:183], v[86:87], off offset:512
	global_load_dwordx4 v[184:187], v[86:87], off offset:528
	global_load_dwordx4 v[124:127], v[90:91], off offset:64
	global_load_dwordx4 v[128:131], v[90:91], off offset:80
	global_load_dwordx4 v[188:191], v[86:87], off offset:576
	global_load_dwordx4 v[192:195], v[86:87], off offset:592
	global_load_dwordx4 v[132:135], v[90:91], off offset:128
	global_load_dwordx4 v[136:139], v[90:91], off offset:144
	global_load_dwordx4 v[196:199], v[86:87], off offset:640
	global_load_dwordx4 v[200:203], v[86:87], off offset:656
	global_load_dwordx4 v[140:143], v[90:91], off offset:192
	global_load_dwordx4 v[144:147], v[90:91], off offset:208
	global_load_dwordx4 v[204:207], v[86:87], off offset:704
	global_load_dwordx4 v[208:211], v[86:87], off offset:720
	global_load_dwordx4 v[148:151], v[90:91], off offset:256
	global_load_dwordx4 v[152:155], v[90:91], off offset:272
	global_load_dwordx4 v[212:215], v[86:87], off offset:768
	global_load_dwordx4 v[220:223], v[86:87], off offset:784
	global_load_dwordx4 v[156:159], v[90:91], off offset:320
	global_load_dwordx4 v[160:163], v[90:91], off offset:336
	global_load_dwordx4 v[224:227], v[86:87], off offset:832
	global_load_dwordx4 v[228:231], v[86:87], off offset:848
	global_load_dwordx4 v[164:167], v[90:91], off offset:384
	global_load_dwordx4 v[168:171], v[90:91], off offset:400
	global_load_dwordx4 v[232:235], v[86:87], off offset:896
	global_load_dwordx4 v[240:243], v[86:87], off offset:912
	global_load_dwordx4 v[172:175], v[90:91], off offset:448
	global_load_dwordx4 v[176:179], v[90:91], off offset:464
	global_load_dwordx4 v[244:247], v[86:87], off offset:960
	global_load_dwordx4 v[248:251], v[86:87], off offset:976
	s_and_b64 s[0:1], s[4:5], exec
	v_readlane_b32 s60, v239, 31
	v_readlane_b32 s61, v239, 32
	s_mov_b64 s[46:47], s[66:67]
	s_cselect_b32 s1, s61, s47
	s_cselect_b32 s0, s60, s46
	s_ashr_i32 s25, s24, 31
	s_lshl_b64 s[24:25], s[24:25], 15
	v_mov_b32_e32 v75, v65
	v_mov_b32_e32 v77, v65
	v_mov_b32_e32 v79, v65
	v_mov_b32_e32 v81, v65
	v_lshl_add_u64 v[92:93], v[70:71], 0, s[24:25]
	s_and_b64 vcc, exec, s[26:27]
	v_readlane_b32 s49, v239, 20
	v_readlane_b32 s50, v239, 21
	v_readlane_b32 s51, v239, 22
	v_readlane_b32 s52, v239, 23
	v_readlane_b32 s53, v239, 24
	v_readlane_b32 s54, v239, 25
	v_readlane_b32 s55, v239, 26
	v_readlane_b32 s56, v239, 27
	v_readlane_b32 s57, v239, 28
	v_readlane_b32 s58, v239, 29
	v_readlane_b32 s59, v239, 30
	v_readlane_b32 s62, v239, 33
	v_readlane_b32 s63, v239, 34
	v_readlane_b32 s65, v239, 36
	v_readlane_b32 s68, v239, 39
	v_readlane_b32 s69, v239, 40
	v_readlane_b32 s70, v239, 41
	v_readlane_b32 s71, v239, 42
	v_readlane_b32 s72, v239, 43
	v_readlane_b32 s73, v239, 44
	v_readlane_b32 s74, v239, 45
	v_readlane_b32 s75, v239, 46
	v_readlane_b32 s76, v239, 47
	v_readlane_b32 s77, v239, 48
	v_readlane_b32 s78, v239, 49
	v_readlane_b32 s79, v239, 50
	s_waitcnt vmcnt(0)
	v_pk_add_f32 v[116:117], v[116:117], v[180:181]
	v_pk_add_f32 v[118:119], v[118:119], v[182:183]
	v_pk_add_f32 v[120:121], v[120:121], v[184:185]
	v_pk_add_f32 v[122:123], v[122:123], v[186:187]
	v_pk_add_f32 v[124:125], v[124:125], v[188:189]
	v_pk_add_f32 v[126:127], v[126:127], v[190:191]
	v_pk_add_f32 v[128:129], v[128:129], v[192:193]
	v_pk_add_f32 v[130:131], v[130:131], v[194:195]
	v_pk_add_f32 v[132:133], v[132:133], v[196:197]
	v_pk_add_f32 v[134:135], v[134:135], v[198:199]
	v_pk_add_f32 v[136:137], v[136:137], v[200:201]
	v_pk_add_f32 v[138:139], v[138:139], v[202:203]
	v_pk_add_f32 v[140:141], v[140:141], v[204:205]
	v_pk_add_f32 v[142:143], v[142:143], v[206:207]
	v_pk_add_f32 v[144:145], v[144:145], v[208:209]
	v_pk_add_f32 v[146:147], v[146:147], v[210:211]
	v_pk_add_f32 v[148:149], v[148:149], v[212:213]
	v_pk_add_f32 v[150:151], v[150:151], v[214:215]
	v_pk_add_f32 v[152:153], v[152:153], v[220:221]
	v_pk_add_f32 v[154:155], v[154:155], v[222:223]
	v_pk_add_f32 v[156:157], v[156:157], v[224:225]
	v_pk_add_f32 v[158:159], v[158:159], v[226:227]
	v_pk_add_f32 v[160:161], v[160:161], v[228:229]
	v_pk_add_f32 v[162:163], v[162:163], v[230:231]
	v_pk_add_f32 v[164:165], v[164:165], v[232:233]
	v_pk_add_f32 v[166:167], v[166:167], v[234:235]
	v_pk_add_f32 v[168:169], v[168:169], v[240:241]
	v_pk_add_f32 v[170:171], v[170:171], v[242:243]
	v_pk_add_f32 v[172:173], v[172:173], v[244:245]
	v_pk_add_f32 v[174:175], v[174:175], v[246:247]
	v_pk_add_f32 v[176:177], v[176:177], v[248:249]
	v_pk_add_f32 v[178:179], v[178:179], v[250:251]
	v_lshl_add_u64 v[248:249], v[92:93], 0, v[74:75]
	v_lshl_add_u64 v[250:251], v[92:93], 0, v[76:77]
	v_lshl_add_u64 v[252:253], v[92:93], 0, v[78:79]
	v_lshl_add_u64 v[254:255], v[92:93], 0, v[80:81]
	global_load_dwordx4 v[220:223], v72, s[0:1]
	global_load_dwordx4 v[224:227], v72, s[0:1] offset:16
	global_load_dwordx4 v[180:183], v[248:249], off
	global_load_dwordx4 v[184:187], v[250:251], off
	global_load_dwordx4 v[188:191], v[252:253], off
	global_load_dwordx4 v[192:195], v[254:255], off
	global_load_dwordx4 v[228:231], v72, s[0:1] offset:64
	global_load_dwordx4 v[232:235], v72, s[0:1] offset:80
	global_load_dwordx4 v[196:199], v[248:249], off offset:32
	global_load_dwordx4 v[200:203], v[250:251], off offset:32
	global_load_dwordx4 v[204:207], v[252:253], off offset:32
	global_load_dwordx4 v[208:211], v[254:255], off offset:32
	s_waitcnt vmcnt(6)
	v_pk_add_f32 v[116:117], v[116:117], v[220:221]
	v_pk_add_f32 v[118:119], v[118:119], v[222:223]
	v_pk_add_f32 v[120:121], v[120:121], v[224:225]
	v_pk_add_f32 v[122:123], v[122:123], v[226:227]
	v_mul_f32_e32 v212, 0xbfb8aa3b, v116
	v_mul_f32_e32 v213, 0xbfb8aa3b, v117
	v_mul_f32_e32 v214, 0xbfb8aa3b, v118
	v_mul_f32_e32 v215, 0xbfb8aa3b, v119
	v_mul_f32_e32 v244, 0xbfb8aa3b, v120
	v_mul_f32_e32 v245, 0xbfb8aa3b, v121
	v_mul_f32_e32 v246, 0xbfb8aa3b, v122
	v_mul_f32_e32 v247, 0xbfb8aa3b, v123
	v_exp_f32_e32 v212, v212
	v_exp_f32_e32 v213, v213
	v_exp_f32_e32 v214, v214
	v_exp_f32_e32 v215, v215
	v_exp_f32_e32 v244, v244
	v_exp_f32_e32 v245, v245
	v_exp_f32_e32 v246, v246
	v_exp_f32_e32 v247, v247
	v_add_f32_e32 v212, 1.0, v212
	v_add_f32_e32 v213, 1.0, v213
	v_add_f32_e32 v214, 1.0, v214
	v_add_f32_e32 v215, 1.0, v215
	v_add_f32_e32 v244, 1.0, v244
	v_add_f32_e32 v245, 1.0, v245
	v_add_f32_e32 v246, 1.0, v246
	v_add_f32_e32 v247, 1.0, v247
	v_rcp_f32_e32 v212, v212
	v_rcp_f32_e32 v213, v213
	v_rcp_f32_e32 v214, v214
	v_rcp_f32_e32 v215, v215
	v_rcp_f32_e32 v244, v244
	v_rcp_f32_e32 v245, v245
	v_rcp_f32_e32 v246, v246
	v_rcp_f32_e32 v247, v247
	v_pk_mul_f32 v[116:117], v[116:117], v[212:213]
	v_pk_mul_f32 v[118:119], v[118:119], v[214:215]
	v_pk_mul_f32 v[120:121], v[120:121], v[244:245]
	v_pk_mul_f32 v[122:123], v[122:123], v[246:247]
	v_cvt_pk_bf16_f32 v240, v116, v117
	v_cvt_pk_bf16_f32 v241, v118, v119
	v_cvt_pk_bf16_f32 v242, v120, v121
	v_cvt_pk_bf16_f32 v243, v122, v123
	s_nop 1
	v_mfma_f32_32x32x16_bf16 v[48:63], v[180:183], v[240:243], 0
	v_mfma_f32_32x32x16_bf16 v[32:47], v[184:187], v[240:243], 0
	v_mfma_f32_32x32x16_bf16 v[16:31], v[188:191], v[240:243], 0
	v_mfma_f32_32x32x16_bf16 v[0:15], v[192:195], v[240:243], 0
	global_load_dwordx4 v[220:223], v72, s[0:1] offset:128
	global_load_dwordx4 v[224:227], v72, s[0:1] offset:144
	global_load_dwordx4 v[180:183], v[248:249], off offset:64
	global_load_dwordx4 v[184:187], v[250:251], off offset:64
	global_load_dwordx4 v[188:191], v[252:253], off offset:64
	global_load_dwordx4 v[192:195], v[254:255], off offset:64
	s_waitcnt vmcnt(6)
	v_pk_add_f32 v[124:125], v[124:125], v[228:229]
	v_pk_add_f32 v[126:127], v[126:127], v[230:231]
	v_pk_add_f32 v[128:129], v[128:129], v[232:233]
	v_pk_add_f32 v[130:131], v[130:131], v[234:235]
	v_mul_f32_e32 v212, 0xbfb8aa3b, v124
	v_mul_f32_e32 v213, 0xbfb8aa3b, v125
	v_mul_f32_e32 v214, 0xbfb8aa3b, v126
	v_mul_f32_e32 v215, 0xbfb8aa3b, v127
	v_mul_f32_e32 v244, 0xbfb8aa3b, v128
	v_mul_f32_e32 v245, 0xbfb8aa3b, v129
	v_mul_f32_e32 v246, 0xbfb8aa3b, v130
	v_mul_f32_e32 v247, 0xbfb8aa3b, v131
	v_exp_f32_e32 v212, v212
	v_exp_f32_e32 v213, v213
	v_exp_f32_e32 v214, v214
	v_exp_f32_e32 v215, v215
	v_exp_f32_e32 v244, v244
	v_exp_f32_e32 v245, v245
	v_exp_f32_e32 v246, v246
	v_exp_f32_e32 v247, v247
	v_add_f32_e32 v212, 1.0, v212
	v_add_f32_e32 v213, 1.0, v213
	v_add_f32_e32 v214, 1.0, v214
	v_add_f32_e32 v215, 1.0, v215
	v_add_f32_e32 v244, 1.0, v244
	v_add_f32_e32 v245, 1.0, v245
	v_add_f32_e32 v246, 1.0, v246
	v_add_f32_e32 v247, 1.0, v247
	v_rcp_f32_e32 v212, v212
	v_rcp_f32_e32 v213, v213
	v_rcp_f32_e32 v214, v214
	v_rcp_f32_e32 v215, v215
	v_rcp_f32_e32 v244, v244
	v_rcp_f32_e32 v245, v245
	v_rcp_f32_e32 v246, v246
	v_rcp_f32_e32 v247, v247
	v_pk_mul_f32 v[124:125], v[124:125], v[212:213]
	v_pk_mul_f32 v[126:127], v[126:127], v[214:215]
	v_pk_mul_f32 v[128:129], v[128:129], v[244:245]
	v_pk_mul_f32 v[130:131], v[130:131], v[246:247]
	v_cvt_pk_bf16_f32 v240, v124, v125
	v_cvt_pk_bf16_f32 v241, v126, v127
	v_cvt_pk_bf16_f32 v242, v128, v129
	v_cvt_pk_bf16_f32 v243, v130, v131
	s_nop 1
	v_mfma_f32_32x32x16_bf16 v[48:63], v[196:199], v[240:243], v[48:63]
	v_mfma_f32_32x32x16_bf16 v[32:47], v[200:203], v[240:243], v[32:47]
	v_mfma_f32_32x32x16_bf16 v[16:31], v[204:207], v[240:243], v[16:31]
	v_mfma_f32_32x32x16_bf16 v[0:15], v[208:211], v[240:243], v[0:15]
	global_load_dwordx4 v[228:231], v72, s[0:1] offset:192
	global_load_dwordx4 v[232:235], v72, s[0:1] offset:208
	global_load_dwordx4 v[196:199], v[248:249], off offset:96
	global_load_dwordx4 v[200:203], v[250:251], off offset:96
	global_load_dwordx4 v[204:207], v[252:253], off offset:96
	global_load_dwordx4 v[208:211], v[254:255], off offset:96
	s_waitcnt vmcnt(6)
	v_pk_add_f32 v[132:133], v[132:133], v[220:221]
	v_pk_add_f32 v[134:135], v[134:135], v[222:223]
	v_pk_add_f32 v[136:137], v[136:137], v[224:225]
	v_pk_add_f32 v[138:139], v[138:139], v[226:227]
	v_mul_f32_e32 v212, 0xbfb8aa3b, v132
	v_mul_f32_e32 v213, 0xbfb8aa3b, v133
	v_mul_f32_e32 v214, 0xbfb8aa3b, v134
	v_mul_f32_e32 v215, 0xbfb8aa3b, v135
	v_mul_f32_e32 v244, 0xbfb8aa3b, v136
	v_mul_f32_e32 v245, 0xbfb8aa3b, v137
	v_mul_f32_e32 v246, 0xbfb8aa3b, v138
	v_mul_f32_e32 v247, 0xbfb8aa3b, v139
	v_exp_f32_e32 v212, v212
	v_exp_f32_e32 v213, v213
	v_exp_f32_e32 v214, v214
	v_exp_f32_e32 v215, v215
	v_exp_f32_e32 v244, v244
	v_exp_f32_e32 v245, v245
	v_exp_f32_e32 v246, v246
	v_exp_f32_e32 v247, v247
	v_add_f32_e32 v212, 1.0, v212
	v_add_f32_e32 v213, 1.0, v213
	v_add_f32_e32 v214, 1.0, v214
	v_add_f32_e32 v215, 1.0, v215
	v_add_f32_e32 v244, 1.0, v244
	v_add_f32_e32 v245, 1.0, v245
	v_add_f32_e32 v246, 1.0, v246
	v_add_f32_e32 v247, 1.0, v247
	v_rcp_f32_e32 v212, v212
	v_rcp_f32_e32 v213, v213
	v_rcp_f32_e32 v214, v214
	v_rcp_f32_e32 v215, v215
	v_rcp_f32_e32 v244, v244
	v_rcp_f32_e32 v245, v245
	v_rcp_f32_e32 v246, v246
	v_rcp_f32_e32 v247, v247
	v_pk_mul_f32 v[132:133], v[132:133], v[212:213]
	v_pk_mul_f32 v[134:135], v[134:135], v[214:215]
	v_pk_mul_f32 v[136:137], v[136:137], v[244:245]
	v_pk_mul_f32 v[138:139], v[138:139], v[246:247]
	v_cvt_pk_bf16_f32 v240, v132, v133
	v_cvt_pk_bf16_f32 v241, v134, v135
	v_cvt_pk_bf16_f32 v242, v136, v137
	v_cvt_pk_bf16_f32 v243, v138, v139
	s_nop 1
	v_mfma_f32_32x32x16_bf16 v[48:63], v[180:183], v[240:243], v[48:63]
	v_mfma_f32_32x32x16_bf16 v[32:47], v[184:187], v[240:243], v[32:47]
	v_mfma_f32_32x32x16_bf16 v[16:31], v[188:191], v[240:243], v[16:31]
	v_mfma_f32_32x32x16_bf16 v[0:15], v[192:195], v[240:243], v[0:15]
	global_load_dwordx4 v[220:223], v72, s[0:1] offset:256
	global_load_dwordx4 v[224:227], v72, s[0:1] offset:272
	global_load_dwordx4 v[180:183], v[248:249], off offset:128
	global_load_dwordx4 v[184:187], v[250:251], off offset:128
	global_load_dwordx4 v[188:191], v[252:253], off offset:128
	global_load_dwordx4 v[192:195], v[254:255], off offset:128
	s_waitcnt vmcnt(6)
	v_pk_add_f32 v[140:141], v[140:141], v[228:229]
	v_pk_add_f32 v[142:143], v[142:143], v[230:231]
	v_pk_add_f32 v[144:145], v[144:145], v[232:233]
	v_pk_add_f32 v[146:147], v[146:147], v[234:235]
	v_mul_f32_e32 v212, 0xbfb8aa3b, v140
	v_mul_f32_e32 v213, 0xbfb8aa3b, v141
	v_mul_f32_e32 v214, 0xbfb8aa3b, v142
	v_mul_f32_e32 v215, 0xbfb8aa3b, v143
	v_mul_f32_e32 v244, 0xbfb8aa3b, v144
	v_mul_f32_e32 v245, 0xbfb8aa3b, v145
	v_mul_f32_e32 v246, 0xbfb8aa3b, v146
	v_mul_f32_e32 v247, 0xbfb8aa3b, v147
	v_exp_f32_e32 v212, v212
	v_exp_f32_e32 v213, v213
	v_exp_f32_e32 v214, v214
	v_exp_f32_e32 v215, v215
	v_exp_f32_e32 v244, v244
	v_exp_f32_e32 v245, v245
	v_exp_f32_e32 v246, v246
	v_exp_f32_e32 v247, v247
	v_add_f32_e32 v212, 1.0, v212
	v_add_f32_e32 v213, 1.0, v213
	v_add_f32_e32 v214, 1.0, v214
	v_add_f32_e32 v215, 1.0, v215
	v_add_f32_e32 v244, 1.0, v244
	v_add_f32_e32 v245, 1.0, v245
	v_add_f32_e32 v246, 1.0, v246
	v_add_f32_e32 v247, 1.0, v247
	v_rcp_f32_e32 v212, v212
	v_rcp_f32_e32 v213, v213
	v_rcp_f32_e32 v214, v214
	v_rcp_f32_e32 v215, v215
	v_rcp_f32_e32 v244, v244
	v_rcp_f32_e32 v245, v245
	v_rcp_f32_e32 v246, v246
	v_rcp_f32_e32 v247, v247
	v_pk_mul_f32 v[140:141], v[140:141], v[212:213]
	v_pk_mul_f32 v[142:143], v[142:143], v[214:215]
	v_pk_mul_f32 v[144:145], v[144:145], v[244:245]
	v_pk_mul_f32 v[146:147], v[146:147], v[246:247]
	v_cvt_pk_bf16_f32 v240, v140, v141
	v_cvt_pk_bf16_f32 v241, v142, v143
	v_cvt_pk_bf16_f32 v242, v144, v145
	v_cvt_pk_bf16_f32 v243, v146, v147
	s_nop 1
	v_mfma_f32_32x32x16_bf16 v[48:63], v[196:199], v[240:243], v[48:63]
	v_mfma_f32_32x32x16_bf16 v[32:47], v[200:203], v[240:243], v[32:47]
	v_mfma_f32_32x32x16_bf16 v[16:31], v[204:207], v[240:243], v[16:31]
	v_mfma_f32_32x32x16_bf16 v[0:15], v[208:211], v[240:243], v[0:15]
	global_load_dwordx4 v[228:231], v72, s[0:1] offset:320
	global_load_dwordx4 v[232:235], v72, s[0:1] offset:336
	global_load_dwordx4 v[196:199], v[248:249], off offset:160
	global_load_dwordx4 v[200:203], v[250:251], off offset:160
	global_load_dwordx4 v[204:207], v[252:253], off offset:160
	global_load_dwordx4 v[208:211], v[254:255], off offset:160
	s_waitcnt vmcnt(6)
	v_pk_add_f32 v[148:149], v[148:149], v[220:221]
	v_pk_add_f32 v[150:151], v[150:151], v[222:223]
	v_pk_add_f32 v[152:153], v[152:153], v[224:225]
	v_pk_add_f32 v[154:155], v[154:155], v[226:227]
	v_mul_f32_e32 v212, 0xbfb8aa3b, v148
	v_mul_f32_e32 v213, 0xbfb8aa3b, v149
	v_mul_f32_e32 v214, 0xbfb8aa3b, v150
	v_mul_f32_e32 v215, 0xbfb8aa3b, v151
	v_mul_f32_e32 v244, 0xbfb8aa3b, v152
	v_mul_f32_e32 v245, 0xbfb8aa3b, v153
	v_mul_f32_e32 v246, 0xbfb8aa3b, v154
	v_mul_f32_e32 v247, 0xbfb8aa3b, v155
	v_exp_f32_e32 v212, v212
	v_exp_f32_e32 v213, v213
	v_exp_f32_e32 v214, v214
	v_exp_f32_e32 v215, v215
	v_exp_f32_e32 v244, v244
	v_exp_f32_e32 v245, v245
	v_exp_f32_e32 v246, v246
	v_exp_f32_e32 v247, v247
	v_add_f32_e32 v212, 1.0, v212
	v_add_f32_e32 v213, 1.0, v213
	v_add_f32_e32 v214, 1.0, v214
	v_add_f32_e32 v215, 1.0, v215
	v_add_f32_e32 v244, 1.0, v244
	v_add_f32_e32 v245, 1.0, v245
	v_add_f32_e32 v246, 1.0, v246
	v_add_f32_e32 v247, 1.0, v247
	v_rcp_f32_e32 v212, v212
	v_rcp_f32_e32 v213, v213
	v_rcp_f32_e32 v214, v214
	v_rcp_f32_e32 v215, v215
	v_rcp_f32_e32 v244, v244
	v_rcp_f32_e32 v245, v245
	v_rcp_f32_e32 v246, v246
	v_rcp_f32_e32 v247, v247
	v_pk_mul_f32 v[148:149], v[148:149], v[212:213]
	v_pk_mul_f32 v[150:151], v[150:151], v[214:215]
	v_pk_mul_f32 v[152:153], v[152:153], v[244:245]
	v_pk_mul_f32 v[154:155], v[154:155], v[246:247]
	v_cvt_pk_bf16_f32 v240, v148, v149
	v_cvt_pk_bf16_f32 v241, v150, v151
	v_cvt_pk_bf16_f32 v242, v152, v153
	v_cvt_pk_bf16_f32 v243, v154, v155
	s_nop 1
	v_mfma_f32_32x32x16_bf16 v[48:63], v[180:183], v[240:243], v[48:63]
	v_mfma_f32_32x32x16_bf16 v[32:47], v[184:187], v[240:243], v[32:47]
	v_mfma_f32_32x32x16_bf16 v[16:31], v[188:191], v[240:243], v[16:31]
	v_mfma_f32_32x32x16_bf16 v[0:15], v[192:195], v[240:243], v[0:15]
	global_load_dwordx4 v[220:223], v72, s[0:1] offset:384
	global_load_dwordx4 v[224:227], v72, s[0:1] offset:400
	global_load_dwordx4 v[180:183], v[248:249], off offset:192
	global_load_dwordx4 v[184:187], v[250:251], off offset:192
	global_load_dwordx4 v[188:191], v[252:253], off offset:192
	global_load_dwordx4 v[192:195], v[254:255], off offset:192
	s_waitcnt vmcnt(6)
	v_pk_add_f32 v[156:157], v[156:157], v[228:229]
	v_pk_add_f32 v[158:159], v[158:159], v[230:231]
	v_pk_add_f32 v[160:161], v[160:161], v[232:233]
	v_pk_add_f32 v[162:163], v[162:163], v[234:235]
	v_mul_f32_e32 v212, 0xbfb8aa3b, v156
	v_mul_f32_e32 v213, 0xbfb8aa3b, v157
	v_mul_f32_e32 v214, 0xbfb8aa3b, v158
	v_mul_f32_e32 v215, 0xbfb8aa3b, v159
	v_mul_f32_e32 v244, 0xbfb8aa3b, v160
	v_mul_f32_e32 v245, 0xbfb8aa3b, v161
	v_mul_f32_e32 v246, 0xbfb8aa3b, v162
	v_mul_f32_e32 v247, 0xbfb8aa3b, v163
	v_exp_f32_e32 v212, v212
	v_exp_f32_e32 v213, v213
	v_exp_f32_e32 v214, v214
	v_exp_f32_e32 v215, v215
	v_exp_f32_e32 v244, v244
	v_exp_f32_e32 v245, v245
	v_exp_f32_e32 v246, v246
	v_exp_f32_e32 v247, v247
	v_add_f32_e32 v212, 1.0, v212
	v_add_f32_e32 v213, 1.0, v213
	v_add_f32_e32 v214, 1.0, v214
	v_add_f32_e32 v215, 1.0, v215
	v_add_f32_e32 v244, 1.0, v244
	v_add_f32_e32 v245, 1.0, v245
	v_add_f32_e32 v246, 1.0, v246
	v_add_f32_e32 v247, 1.0, v247
	v_rcp_f32_e32 v212, v212
	v_rcp_f32_e32 v213, v213
	v_rcp_f32_e32 v214, v214
	v_rcp_f32_e32 v215, v215
	v_rcp_f32_e32 v244, v244
	v_rcp_f32_e32 v245, v245
	v_rcp_f32_e32 v246, v246
	v_rcp_f32_e32 v247, v247
	v_pk_mul_f32 v[156:157], v[156:157], v[212:213]
	v_pk_mul_f32 v[158:159], v[158:159], v[214:215]
	v_pk_mul_f32 v[160:161], v[160:161], v[244:245]
	v_pk_mul_f32 v[162:163], v[162:163], v[246:247]
	v_cvt_pk_bf16_f32 v240, v156, v157
	v_cvt_pk_bf16_f32 v241, v158, v159
	v_cvt_pk_bf16_f32 v242, v160, v161
	v_cvt_pk_bf16_f32 v243, v162, v163
	s_nop 1
	v_mfma_f32_32x32x16_bf16 v[48:63], v[196:199], v[240:243], v[48:63]
	v_mfma_f32_32x32x16_bf16 v[32:47], v[200:203], v[240:243], v[32:47]
	v_mfma_f32_32x32x16_bf16 v[16:31], v[204:207], v[240:243], v[16:31]
	v_mfma_f32_32x32x16_bf16 v[0:15], v[208:211], v[240:243], v[0:15]
	global_load_dwordx4 v[228:231], v72, s[0:1] offset:448
	global_load_dwordx4 v[232:235], v72, s[0:1] offset:464
	global_load_dwordx4 v[196:199], v[248:249], off offset:224
	global_load_dwordx4 v[200:203], v[250:251], off offset:224
	global_load_dwordx4 v[204:207], v[252:253], off offset:224
	global_load_dwordx4 v[208:211], v[254:255], off offset:224
	s_waitcnt vmcnt(6)
	v_pk_add_f32 v[164:165], v[164:165], v[220:221]
	v_pk_add_f32 v[166:167], v[166:167], v[222:223]
	v_pk_add_f32 v[168:169], v[168:169], v[224:225]
	v_pk_add_f32 v[170:171], v[170:171], v[226:227]
	v_mul_f32_e32 v212, 0xbfb8aa3b, v164
	v_mul_f32_e32 v213, 0xbfb8aa3b, v165
	v_mul_f32_e32 v214, 0xbfb8aa3b, v166
	v_mul_f32_e32 v215, 0xbfb8aa3b, v167
	v_mul_f32_e32 v244, 0xbfb8aa3b, v168
	v_mul_f32_e32 v245, 0xbfb8aa3b, v169
	v_mul_f32_e32 v246, 0xbfb8aa3b, v170
	v_mul_f32_e32 v247, 0xbfb8aa3b, v171
	v_exp_f32_e32 v212, v212
	v_exp_f32_e32 v213, v213
	v_exp_f32_e32 v214, v214
	v_exp_f32_e32 v215, v215
	v_exp_f32_e32 v244, v244
	v_exp_f32_e32 v245, v245
	v_exp_f32_e32 v246, v246
	v_exp_f32_e32 v247, v247
	v_add_f32_e32 v212, 1.0, v212
	v_add_f32_e32 v213, 1.0, v213
	v_add_f32_e32 v214, 1.0, v214
	v_add_f32_e32 v215, 1.0, v215
	v_add_f32_e32 v244, 1.0, v244
	v_add_f32_e32 v245, 1.0, v245
	v_add_f32_e32 v246, 1.0, v246
	v_add_f32_e32 v247, 1.0, v247
	v_rcp_f32_e32 v212, v212
	v_rcp_f32_e32 v213, v213
	v_rcp_f32_e32 v214, v214
	v_rcp_f32_e32 v215, v215
	v_rcp_f32_e32 v244, v244
	v_rcp_f32_e32 v245, v245
	v_rcp_f32_e32 v246, v246
	v_rcp_f32_e32 v247, v247
	v_pk_mul_f32 v[164:165], v[164:165], v[212:213]
	v_pk_mul_f32 v[166:167], v[166:167], v[214:215]
	v_pk_mul_f32 v[168:169], v[168:169], v[244:245]
	v_pk_mul_f32 v[170:171], v[170:171], v[246:247]
	v_cvt_pk_bf16_f32 v240, v164, v165
	v_cvt_pk_bf16_f32 v241, v166, v167
	v_cvt_pk_bf16_f32 v242, v168, v169
	v_cvt_pk_bf16_f32 v243, v170, v171
	s_nop 1
	v_mfma_f32_32x32x16_bf16 v[48:63], v[180:183], v[240:243], v[48:63]
	v_mfma_f32_32x32x16_bf16 v[32:47], v[184:187], v[240:243], v[32:47]
	v_mfma_f32_32x32x16_bf16 v[16:31], v[188:191], v[240:243], v[16:31]
	v_mfma_f32_32x32x16_bf16 v[0:15], v[192:195], v[240:243], v[0:15]
	s_waitcnt vmcnt(0)
	v_pk_add_f32 v[172:173], v[172:173], v[228:229]
	v_pk_add_f32 v[174:175], v[174:175], v[230:231]
	v_pk_add_f32 v[176:177], v[176:177], v[232:233]
	v_pk_add_f32 v[178:179], v[178:179], v[234:235]
	v_mul_f32_e32 v212, 0xbfb8aa3b, v172
	v_mul_f32_e32 v213, 0xbfb8aa3b, v173
	v_mul_f32_e32 v214, 0xbfb8aa3b, v174
	v_mul_f32_e32 v215, 0xbfb8aa3b, v175
	v_mul_f32_e32 v244, 0xbfb8aa3b, v176
	v_mul_f32_e32 v245, 0xbfb8aa3b, v177
	v_mul_f32_e32 v246, 0xbfb8aa3b, v178
	v_mul_f32_e32 v247, 0xbfb8aa3b, v179
	v_exp_f32_e32 v212, v212
	v_exp_f32_e32 v213, v213
	v_exp_f32_e32 v214, v214
	v_exp_f32_e32 v215, v215
	v_exp_f32_e32 v244, v244
	v_exp_f32_e32 v245, v245
	v_exp_f32_e32 v246, v246
	v_exp_f32_e32 v247, v247
	v_add_f32_e32 v212, 1.0, v212
	v_add_f32_e32 v213, 1.0, v213
	v_add_f32_e32 v214, 1.0, v214
	v_add_f32_e32 v215, 1.0, v215
	v_add_f32_e32 v244, 1.0, v244
	v_add_f32_e32 v245, 1.0, v245
	v_add_f32_e32 v246, 1.0, v246
	v_add_f32_e32 v247, 1.0, v247
	v_rcp_f32_e32 v212, v212
	v_rcp_f32_e32 v213, v213
	v_rcp_f32_e32 v214, v214
	v_rcp_f32_e32 v215, v215
	v_rcp_f32_e32 v244, v244
	v_rcp_f32_e32 v245, v245
	v_rcp_f32_e32 v246, v246
	v_rcp_f32_e32 v247, v247
	v_pk_mul_f32 v[172:173], v[172:173], v[212:213]
	v_pk_mul_f32 v[174:175], v[174:175], v[214:215]
	v_pk_mul_f32 v[176:177], v[176:177], v[244:245]
	v_pk_mul_f32 v[178:179], v[178:179], v[246:247]
	v_cvt_pk_bf16_f32 v240, v172, v173
	v_cvt_pk_bf16_f32 v241, v174, v175
	v_cvt_pk_bf16_f32 v242, v176, v177
	v_cvt_pk_bf16_f32 v243, v178, v179
	global_load_dwordx4 v[180:183], v[68:69], off
	global_load_dwordx4 v[120:123], v[68:69], off offset:32
	global_load_dwordx4 v[124:127], v[68:69], off offset:64
	global_load_dwordx4 v[128:131], v[68:69], off offset:96
	global_load_dwordx4 v[132:135], v[68:69], off offset:128
	global_load_dwordx4 v[136:139], v[68:69], off offset:160
	global_load_dwordx4 v[140:143], v[68:69], off offset:192
	global_load_dwordx4 v[144:147], v[68:69], off offset:224
	global_load_dwordx4 v[148:151], v[68:69], off offset:256
	global_load_dwordx4 v[152:155], v[68:69], off offset:288
	global_load_dwordx4 v[156:159], v[68:69], off offset:320
	global_load_dwordx4 v[160:163], v[68:69], off offset:352
	global_load_dwordx4 v[164:167], v[68:69], off offset:384
	global_load_dwordx4 v[168:171], v[68:69], off offset:416
	global_load_dwordx4 v[172:175], v[68:69], off offset:448
	global_load_dwordx4 v[176:179], v[68:69], off offset:480
	v_mov_b32_e32 v86, 1.0
	s_nop 1
	v_mfma_f32_32x32x16_bf16 v[32:47], v[200:203], v[240:243], v[32:47]
	v_mfma_f32_32x32x16_bf16 v[48:63], v[196:199], v[240:243], v[48:63]
	v_mfma_f32_32x32x16_bf16 v[16:31], v[204:207], v[240:243], v[16:31]
	v_mfma_f32_32x32x16_bf16 v[0:15], v[208:211], v[240:243], v[0:15]
	s_cbranch_vccz .LBB0_1075
	v_cmp_ge_i32_e32 vcc, s28, v115
	s_and_saveexec_b64 s[24:25], vcc
	s_cbranch_execz .LBB0_1060
	s_branch .LBB0_1076

.LBB0_1076:
	v_cndmask_b32_e64 v64, 0, 1, s[4:5]
	s_nop 2
	v_pk_mul_f32 v[48:49], v[48:49], v[86:87] op_sel_hi:[1,0]
	v_cmp_ne_u32_e64 s[0:1], 1, v64
	s_andn2_b64 vcc, exec, s[4:5]
	v_pk_mul_f32 v[50:51], v[50:51], v[86:87] op_sel_hi:[1,0]
	s_cbranch_vccnz .LBB0_1078
	s_waitcnt vmcnt(0)
	v_mov_b64_e32 v[90:91], v[180:181]
	v_mov_b64_e32 v[92:93], v[182:183]
	v_pk_mul_f32 v[50:51], v[50:51], v[92:93]
	v_pk_mul_f32 v[48:49], v[48:49], v[90:91]

.LBB0_1088:
	v_mov_b64_e32 v[52:53], v[120:121]
	v_mov_b64_e32 v[54:55], v[122:123]
	v_pk_mul_f32 v[50:51], v[50:51], v[54:55]
	v_pk_mul_f32 v[48:49], v[48:49], v[52:53]
	s_and_b64 vcc, exec, s[4:5]
	s_mov_b64 s[6:7], -1
	s_cbranch_vccnz .LBB0_1087

.LBB0_1097:
	v_mov_b64_e32 v[52:53], v[124:125]
	v_mov_b64_e32 v[54:55], v[126:127]
	v_pk_mul_f32 v[50:51], v[50:51], v[54:55]
	v_pk_mul_f32 v[48:49], v[48:49], v[52:53]
	s_and_b64 vcc, exec, s[4:5]
	s_mov_b64 s[26:27], -1
	s_cbranch_vccnz .LBB0_1096

.LBB0_1106:
	v_mov_b64_e32 v[52:53], v[128:129]
	v_mov_b64_e32 v[54:55], v[130:131]
	v_pk_mul_f32 v[50:51], v[50:51], v[54:55]
	v_pk_mul_f32 v[48:49], v[48:49], v[52:53]
	s_and_b64 vcc, exec, s[4:5]
	s_mov_b64 s[26:27], -1
	s_cbranch_vccnz .LBB0_1105

.LBB0_1115:
	v_mov_b64_e32 v[48:49], v[132:133]
	v_mov_b64_e32 v[50:51], v[134:135]
	v_pk_mul_f32 v[34:35], v[34:35], v[50:51]
	v_pk_mul_f32 v[32:33], v[32:33], v[48:49]
	s_and_b64 vcc, exec, s[4:5]
	s_mov_b64 s[26:27], -1
	s_cbranch_vccnz .LBB0_1114

.LBB0_1124:
	v_mov_b64_e32 v[36:37], v[136:137]
	v_mov_b64_e32 v[38:39], v[138:139]
	v_pk_mul_f32 v[34:35], v[34:35], v[38:39]
	v_pk_mul_f32 v[32:33], v[32:33], v[36:37]
	s_and_b64 vcc, exec, s[4:5]
	s_mov_b64 s[26:27], -1
	s_cbranch_vccnz .LBB0_1123

.LBB0_1133:
	v_mov_b64_e32 v[36:37], v[140:141]
	v_mov_b64_e32 v[38:39], v[142:143]
	v_pk_mul_f32 v[34:35], v[34:35], v[38:39]
	v_pk_mul_f32 v[32:33], v[32:33], v[36:37]
	s_and_b64 vcc, exec, s[4:5]
	s_mov_b64 s[26:27], -1
	s_cbranch_vccnz .LBB0_1132

.LBB0_1142:
	v_mov_b64_e32 v[36:37], v[144:145]
	v_mov_b64_e32 v[38:39], v[146:147]
	v_pk_mul_f32 v[34:35], v[34:35], v[38:39]
	v_pk_mul_f32 v[32:33], v[32:33], v[36:37]
	s_and_b64 vcc, exec, s[4:5]
	s_mov_b64 s[26:27], -1
	s_cbranch_vccnz .LBB0_1141

.LBB0_1151:
	v_mov_b64_e32 v[32:33], v[148:149]
	v_mov_b64_e32 v[34:35], v[150:151]
	v_pk_mul_f32 v[18:19], v[18:19], v[34:35]
	v_pk_mul_f32 v[16:17], v[16:17], v[32:33]
	s_and_b64 vcc, exec, s[4:5]
	s_mov_b64 s[26:27], -1
	s_cbranch_vccnz .LBB0_1150

.LBB0_1160:
	v_mov_b64_e32 v[20:21], v[152:153]
	v_mov_b64_e32 v[22:23], v[154:155]
	v_pk_mul_f32 v[18:19], v[18:19], v[22:23]
	v_pk_mul_f32 v[16:17], v[16:17], v[20:21]
	s_and_b64 vcc, exec, s[4:5]
	s_mov_b64 s[26:27], -1
	s_cbranch_vccnz .LBB0_1159

.LBB0_1169:
	v_mov_b64_e32 v[20:21], v[156:157]
	v_mov_b64_e32 v[22:23], v[158:159]
	v_pk_mul_f32 v[18:19], v[18:19], v[22:23]
	v_pk_mul_f32 v[16:17], v[16:17], v[20:21]
	s_and_b64 vcc, exec, s[4:5]
	s_mov_b64 s[26:27], -1
	s_cbranch_vccnz .LBB0_1168

.LBB0_1178:
	v_mov_b64_e32 v[20:21], v[160:161]
	v_mov_b64_e32 v[22:23], v[162:163]
	v_pk_mul_f32 v[18:19], v[18:19], v[22:23]
	v_pk_mul_f32 v[16:17], v[16:17], v[20:21]
	s_and_b64 vcc, exec, s[4:5]
	s_mov_b64 s[26:27], -1
	s_cbranch_vccnz .LBB0_1177

.LBB0_1187:
	v_mov_b64_e32 v[16:17], v[164:165]
	v_mov_b64_e32 v[18:19], v[166:167]
	v_pk_mul_f32 v[2:3], v[2:3], v[18:19]
	v_pk_mul_f32 v[0:1], v[0:1], v[16:17]
	s_and_b64 vcc, exec, s[4:5]
	s_mov_b64 s[26:27], -1
	s_cbranch_vccnz .LBB0_1186

.LBB0_1196:
	v_mov_b64_e32 v[4:5], v[168:169]
	v_mov_b64_e32 v[6:7], v[170:171]
	v_pk_mul_f32 v[2:3], v[2:3], v[6:7]
	v_pk_mul_f32 v[0:1], v[0:1], v[4:5]
	s_and_b64 vcc, exec, s[4:5]
	s_mov_b64 s[26:27], -1
	s_cbranch_vccnz .LBB0_1195

.LBB0_1205:
	v_mov_b64_e32 v[4:5], v[172:173]
	v_mov_b64_e32 v[6:7], v[174:175]
	v_pk_mul_f32 v[2:3], v[2:3], v[6:7]
	v_pk_mul_f32 v[0:1], v[0:1], v[4:5]
	s_and_b64 vcc, exec, s[4:5]
	s_mov_b64 s[26:27], -1
	s_cbranch_vccnz .LBB0_1204

.LBB0_1214:
	v_mov_b64_e32 v[4:5], v[176:177]
	v_mov_b64_e32 v[6:7], v[178:179]
	v_pk_mul_f32 v[2:3], v[2:3], v[6:7]
	v_pk_mul_f32 v[0:1], v[0:1], v[4:5]
	s_and_b64 vcc, exec, s[4:5]
	s_mov_b64 s[0:1], -1
	s_cbranch_vccnz .LBB0_1213

.LBB0_1547:
	s_lshl_b64 s[4:5], 1, s40
	s_waitcnt lgkmcnt(0)
	v_and_b32_e32 v9, s5, v215
	v_and_b32_e32 v8, s4, v214
	v_cmp_ne_u64_e32 vcc, 0, v[8:9]
	s_add_i32 s40, s59, s68
	s_or_b64 s[4:5], s[6:7], vcc
	s_sub_i32 s36, s40, 63
	s_cmpk_gt_i32 s36, 0x1ff
	s_cselect_b64 vcc, -1, 0
	v_cndmask_b32_e64 v8, 0, 1, s[4:5]
	s_and_b64 s[46:47], s[6:7], vcc
	v_cmp_ne_u32_e32 vcc, 0, v8
	s_cmp_eq_u64 vcc, 0
	s_cselect_b64 vcc, -1, 0
	s_or_b64 s[46:47], vcc, s[46:47]
	s_and_b64 vcc, exec, s[46:47]
	s_cbranch_vccnz .LBB0_1534
	s_add_i32 s46, s40, 7
	s_and_b32 s40, s76, 0x18000
	v_add_u32_e32 v8, s40, v232
	ds_read_b128 v[10:13], v8
	ds_read_b128 v[160:163], v8 offset:1024
	ds_read_b128 v[164:167], v8 offset:2048
	ds_read_b128 v[168:171], v8 offset:3072
	ds_read_b128 v[172:175], v8 offset:4096
	s_cmpk_gt_i32 s36, 0x7f
	s_cselect_b64 s[40:41], -1, 0
	s_cmp_lt_i32 s46, s9
	s_cselect_b64 s[46:47], -1, 0
	s_and_b64 s[40:41], s[40:41], s[46:47]
	s_andn2_b64 vcc, exec, s[40:41]
	s_mov_b64 s[40:41], -1
	s_waitcnt lgkmcnt(4)
	v_mfma_f32_32x32x16_bf16 v[144:159], v[10:13], v[176:179], 0
	ds_read_b128 v[10:13], v8 offset:5120
	s_waitcnt lgkmcnt(4)
	v_mfma_f32_32x32x16_bf16 v[144:159], v[160:163], v[180:183], v[144:159]
	ds_read_b128 v[160:163], v8 offset:6144
	s_waitcnt lgkmcnt(4)
	v_mfma_f32_32x32x16_bf16 v[144:159], v[164:167], v[184:187], v[144:159]
	ds_read_b128 v[164:167], v8 offset:7168
	s_waitcnt lgkmcnt(4)
	v_mfma_f32_32x32x16_bf16 v[144:159], v[168:171], v[188:191], v[144:159]
	ds_read_b128 v[240:243], v8 offset:16384
	ds_read_b128 v[244:247], v8 offset:17408
	ds_read_b128 v[248:251], v8 offset:18432
	ds_read_b128 v[252:255], v8 offset:19456
	s_waitcnt lgkmcnt(7)
	v_mfma_f32_32x32x16_bf16 v[144:159], v[172:175], v[192:195], v[144:159]
	s_waitcnt lgkmcnt(6)
	v_mfma_f32_32x32x16_bf16 v[144:159], v[10:13], v[196:199], v[144:159]
	s_waitcnt lgkmcnt(5)
	v_mfma_f32_32x32x16_bf16 v[144:159], v[160:163], v[200:203], v[144:159]
	s_waitcnt lgkmcnt(4)
	v_mfma_f32_32x32x16_bf16 v[144:159], v[164:167], v[204:207], v[144:159]
	s_cbranch_vccz .LBB0_1582
	v_add_u32_e32 v11, s59, v6
	v_add_u32_e32 v14, s59, v7
	s_waitcnt lgkmcnt(0)
	v_min_u32_e32 v10, 0x80, v11
	v_lshl_add_u32 v10, v10, 2, v226
	ds_read_b32 v160, v10
	v_subrev_u32_e32 v12, 1, v11
	v_min_u32_e32 v12, 0x80, v12
	v_lshl_add_u32 v12, v12, 2, v226
	ds_read_b32 v161, v12
	v_subrev_u32_e32 v13, 2, v14
	v_min_u32_e32 v13, 0x80, v13
	v_lshl_add_u32 v13, v13, 2, v226
	ds_read_b32 v162, v13
	v_subrev_u32_e32 v15, 3, v14
	v_min_u32_e32 v15, 0x80, v15
	v_lshl_add_u32 v15, v15, 2, v226
	ds_read_b32 v163, v15
	v_subrev_u32_e32 v10, 8, v11
	v_min_u32_e32 v10, 0x80, v10
	v_lshl_add_u32 v10, v10, 2, v226
	ds_read_b32 v164, v10
	v_subrev_u32_e32 v12, 9, v11
	v_min_u32_e32 v12, 0x80, v12
	v_lshl_add_u32 v12, v12, 2, v226
	ds_read_b32 v165, v12
	v_subrev_u32_e32 v13, 10, v11
	v_min_u32_e32 v13, 0x80, v13
	v_lshl_add_u32 v13, v13, 2, v226
	ds_read_b32 v166, v13
	v_subrev_u32_e32 v15, 11, v11
	v_min_u32_e32 v15, 0x80, v15
	v_lshl_add_u32 v15, v15, 2, v226
	ds_read_b32 v167, v15
	v_subrev_u32_e32 v10, 16, v11
	v_min_u32_e32 v10, 0x80, v10
	v_lshl_add_u32 v10, v10, 2, v226
	ds_read_b32 v168, v10
	v_subrev_u32_e32 v12, 17, v11
	v_min_u32_e32 v12, 0x80, v12
	v_lshl_add_u32 v12, v12, 2, v226
	ds_read_b32 v169, v12
	v_subrev_u32_e32 v13, 18, v11
	v_min_u32_e32 v13, 0x80, v13
	v_lshl_add_u32 v13, v13, 2, v226
	ds_read_b32 v170, v13
	v_subrev_u32_e32 v15, 19, v11
	v_min_u32_e32 v15, 0x80, v15
	v_lshl_add_u32 v15, v15, 2, v226
	ds_read_b32 v171, v15
	s_waitcnt lgkmcnt(11)
	v_add_f32_e32 v160, v144, v160
	v_exp_f32_e32 v160, v160
	v_cmp_gt_u32_e32 vcc, s9, v11
	s_and_b64 vcc, vcc, s[4:5]
	v_cndmask_b32_e32 v160, 0, v160, vcc
	v_add_f32_e32 v9, 0, v160
	v_subrev_u32_e32 v10, 24, v11
	v_min_u32_e32 v10, 0x80, v10
	v_lshl_add_u32 v10, v10, 2, v226
	ds_read_b32 v172, v10
	s_waitcnt lgkmcnt(11)
	v_add_f32_e32 v161, v145, v161
	v_exp_f32_e32 v161, v161
	v_subrev_u32_e32 v12, 1, v11
	v_cmp_gt_u32_e32 vcc, s9, v12
	s_and_b64 vcc, vcc, s[4:5]
	v_cndmask_b32_e32 v161, 0, v161, vcc
	v_add_f32_e32 v9, v9, v161
	v_subrev_u32_e32 v12, 25, v11
	v_min_u32_e32 v12, 0x80, v12
	v_lshl_add_u32 v12, v12, 2, v226
	ds_read_b32 v173, v12
	s_waitcnt lgkmcnt(11)
	v_add_f32_e32 v162, v146, v162
	v_exp_f32_e32 v162, v162
	v_subrev_u32_e32 v13, 2, v14
	v_cmp_gt_u32_e32 vcc, s9, v13
	s_and_b64 vcc, vcc, s[4:5]
	v_cndmask_b32_e32 v162, 0, v162, vcc
	v_add_f32_e32 v9, v9, v162
	v_subrev_u32_e32 v13, 26, v11
	v_min_u32_e32 v13, 0x80, v13
	v_lshl_add_u32 v13, v13, 2, v226
	ds_read_b32 v174, v13
	s_waitcnt lgkmcnt(11)
	v_add_f32_e32 v163, v147, v163
	v_exp_f32_e32 v163, v163
	v_subrev_u32_e32 v15, 3, v14
	v_cmp_gt_u32_e32 vcc, s9, v15
	s_and_b64 vcc, vcc, s[4:5]
	v_cndmask_b32_e32 v163, 0, v163, vcc
	v_add_f32_e32 v9, v9, v163
	v_subrev_u32_e32 v15, 27, v11
	v_min_u32_e32 v15, 0x80, v15
	v_lshl_add_u32 v15, v15, 2, v226
	ds_read_b32 v175, v15
	s_waitcnt lgkmcnt(11)
	v_add_f32_e32 v164, v148, v164
	v_exp_f32_e32 v164, v164
	v_subrev_u32_e32 v10, 8, v11
	v_cmp_gt_u32_e32 vcc, s9, v10
	s_and_b64 vcc, vcc, s[4:5]
	v_cndmask_b32_e32 v164, 0, v164, vcc
	v_add_f32_e32 v9, v9, v164
	s_waitcnt lgkmcnt(10)
	v_add_f32_e32 v165, v149, v165
	v_exp_f32_e32 v165, v165
	v_subrev_u32_e32 v12, 9, v11
	v_cmp_gt_u32_e32 vcc, s9, v12
	s_and_b64 vcc, vcc, s[4:5]
	v_cndmask_b32_e32 v165, 0, v165, vcc
	v_add_f32_e32 v9, v9, v165
	s_waitcnt lgkmcnt(9)
	v_add_f32_e32 v166, v150, v166
	v_exp_f32_e32 v166, v166
	v_subrev_u32_e32 v13, 10, v11
	v_cmp_gt_u32_e32 vcc, s9, v13
	s_and_b64 vcc, vcc, s[4:5]
	v_cndmask_b32_e32 v166, 0, v166, vcc
	v_add_f32_e32 v9, v9, v166
	s_waitcnt lgkmcnt(8)
	v_add_f32_e32 v167, v151, v167
	v_exp_f32_e32 v167, v167
	v_subrev_u32_e32 v15, 11, v11
	v_cmp_gt_u32_e32 vcc, s9, v15
	s_and_b64 vcc, vcc, s[4:5]
	v_cndmask_b32_e32 v167, 0, v167, vcc
	v_add_f32_e32 v9, v9, v167
	s_waitcnt lgkmcnt(7)
	v_add_f32_e32 v168, v152, v168
	v_exp_f32_e32 v168, v168
	v_subrev_u32_e32 v10, 16, v11
	v_cmp_gt_u32_e32 vcc, s9, v10
	s_and_b64 vcc, vcc, s[4:5]
	v_cndmask_b32_e32 v168, 0, v168, vcc
	v_add_f32_e32 v9, v9, v168
	s_waitcnt lgkmcnt(6)
	v_add_f32_e32 v169, v153, v169
	v_exp_f32_e32 v169, v169
	v_subrev_u32_e32 v12, 17, v11
	v_cmp_gt_u32_e32 vcc, s9, v12
	s_and_b64 vcc, vcc, s[4:5]
	v_cndmask_b32_e32 v169, 0, v169, vcc
	v_add_f32_e32 v9, v9, v169
	s_waitcnt lgkmcnt(5)
	v_add_f32_e32 v170, v154, v170
	v_exp_f32_e32 v170, v170
	v_subrev_u32_e32 v13, 18, v11
	v_cmp_gt_u32_e32 vcc, s9, v13
	s_and_b64 vcc, vcc, s[4:5]
	v_cndmask_b32_e32 v170, 0, v170, vcc
	v_add_f32_e32 v9, v9, v170
	s_waitcnt lgkmcnt(4)
	v_add_f32_e32 v171, v155, v171
	v_exp_f32_e32 v171, v171
	v_subrev_u32_e32 v15, 19, v11
	v_cmp_gt_u32_e32 vcc, s9, v15
	s_and_b64 vcc, vcc, s[4:5]
	v_cndmask_b32_e32 v171, 0, v171, vcc
	v_add_f32_e32 v9, v9, v171
	s_waitcnt lgkmcnt(3)
	v_add_f32_e32 v172, v156, v172
	v_exp_f32_e32 v172, v172
	v_subrev_u32_e32 v10, 24, v11
	v_cmp_gt_u32_e32 vcc, s9, v10
	s_and_b64 vcc, vcc, s[4:5]
	v_cndmask_b32_e32 v172, 0, v172, vcc
	v_add_f32_e32 v9, v9, v172
	s_waitcnt lgkmcnt(2)
	v_add_f32_e32 v173, v157, v173
	v_exp_f32_e32 v173, v173
	v_subrev_u32_e32 v12, 25, v11
	v_cmp_gt_u32_e32 vcc, s9, v12
	s_and_b64 vcc, vcc, s[4:5]
	v_cndmask_b32_e32 v173, 0, v173, vcc
	v_add_f32_e32 v9, v9, v173
	s_waitcnt lgkmcnt(1)
	v_add_f32_e32 v174, v158, v174
	v_exp_f32_e32 v174, v174
	v_subrev_u32_e32 v13, 26, v11
	v_cmp_gt_u32_e32 vcc, s9, v13
	s_and_b64 vcc, vcc, s[4:5]
	v_cndmask_b32_e32 v174, 0, v174, vcc
	v_add_f32_e32 v9, v9, v174
	s_waitcnt lgkmcnt(0)
	v_add_f32_e32 v175, v159, v175
	v_exp_f32_e32 v175, v175
	v_subrev_u32_e32 v15, 27, v11
	v_cmp_gt_u32_e32 vcc, s9, v15
	s_and_b64 vcc, vcc, s[4:5]
	v_cndmask_b32_e32 v175, 0, v175, vcc
	v_add_f32_e32 v9, v9, v175
	s_mov_b64 s[40:41], 0
